# phase_post rotary blocks: the two exec-divergent plus/minus variants merged into one branch-free block (sign bit xor-ed into the negated operand for the minus lanes, exec limited to rotating lanes); s
# speedup vs baseline: 1.0113x; 1.0054x over previous
.LBB0_652:
	s_or_b64 exec, exec, s[0:1]
	ds_bpermute_b32 v5, v45, v97
	s_waitcnt lgkmcnt(2)
	ds_read_b64 v[2:3], v108 offset:8
	v_mov_b32_e32 v209, 0x80000000
	v_cmp_gt_i32_e64 s[0:1], 1, v16
	s_nop 1
	v_cndmask_b32_e64 v208, 0, v209, s[0:1]
	v_cmp_gt_i32_e64 s[0:1], 2, v16
	s_and_saveexec_b64 s[22:23], s[0:1]
	v_mov_b32_e32 v6, v97
	s_waitcnt lgkmcnt(0)
	v_mov_b32_e32 v7, v3
	v_mov_b32_e32 v4, v2
	v_mul_f32_e32 v56, v97, v2
	v_xor_b32_e32 v210, v208, v6
	v_xor_b32_e32 v211, v208, v7
	v_pk_fma_f32 v[4:5], v[210:211], v[4:5], v[56:57] op_sel_hi:[1,1,0]
	s_nop 0
	v_mov_b32_e32 v97, v5
	s_or_b64 exec, exec, s[22:23]
	s_waitcnt lgkmcnt(1)
	ds_bpermute_b32 v5, v45, v94
	ds_read_b64 v[6:7], v108 offset:16
	v_mov_b32_e32 v209, 0x80000000
	v_cmp_gt_i32_e64 s[0:1], 1, v16
	s_nop 1
	v_cndmask_b32_e64 v208, 0, v209, s[0:1]
	v_cmp_gt_i32_e64 s[0:1], 2, v16
	s_and_saveexec_b64 s[22:23], s[0:1]
	v_mov_b32_e32 v56, v94
	s_waitcnt lgkmcnt(0)
	v_mov_b32_e32 v57, v7
	v_mov_b32_e32 v4, v6
	v_mul_f32_e32 v58, v7, v5
	v_xor_b32_e32 v210, v208, v58
	v_xor_b32_e32 v211, v208, v59
	v_pk_fma_f32 v[4:5], v[56:57], v[4:5], v[210:211] op_sel_hi:[1,1,0]
	s_nop 0
	v_mov_b32_e32 v94, v4
	s_or_b64 exec, exec, s[22:23]
	ds_bpermute_b32 v57, v45, v95
	s_waitcnt lgkmcnt(2)
	ds_read_b64 v[4:5], v108 offset:24
	v_mov_b32_e32 v209, 0x80000000
	v_cmp_gt_i32_e64 s[0:1], 1, v16
	s_nop 1
	v_cndmask_b32_e64 v208, 0, v209, s[0:1]
	v_cmp_gt_i32_e64 s[0:1], 2, v16
	s_and_saveexec_b64 s[22:23], s[0:1]
	v_mov_b32_e32 v58, v95
	s_waitcnt lgkmcnt(0)
	v_mov_b32_e32 v59, v5
	v_mov_b32_e32 v56, v4
	v_mul_f32_e32 v60, v5, v57
	v_xor_b32_e32 v210, v208, v60
	v_xor_b32_e32 v211, v208, v61
	v_pk_fma_f32 v[56:57], v[58:59], v[56:57], v[210:211] op_sel_hi:[1,1,0]
	s_nop 0
	v_mov_b32_e32 v95, v56
	s_or_b64 exec, exec, s[22:23]
	s_waitcnt lgkmcnt(1)
	ds_bpermute_b32 v57, v45, v92
	ds_read_b64 v[58:59], v108 offset:32
	v_mov_b32_e32 v209, 0x80000000
	v_cmp_gt_i32_e64 s[0:1], 1, v16
	s_nop 1
	v_cndmask_b32_e64 v208, 0, v209, s[0:1]
	v_cmp_gt_i32_e64 s[0:1], 2, v16
	s_and_saveexec_b64 s[22:23], s[0:1]
	v_mov_b32_e32 v60, v92
	s_waitcnt lgkmcnt(0)
	v_mov_b32_e32 v61, v59
	v_mov_b32_e32 v56, v58
	v_mul_f32_e32 v62, v59, v57
	v_xor_b32_e32 v210, v208, v62
	v_xor_b32_e32 v211, v208, v63
	v_pk_fma_f32 v[56:57], v[60:61], v[56:57], v[210:211] op_sel_hi:[1,1,0]
	s_nop 0
	v_mov_b32_e32 v92, v56
	s_or_b64 exec, exec, s[22:23]
	ds_bpermute_b32 v61, v45, v93
	s_waitcnt lgkmcnt(2)
	ds_read_b64 v[56:57], v108 offset:40
	v_mov_b32_e32 v209, 0x80000000
	v_cmp_gt_i32_e64 s[0:1], 1, v16
	s_nop 1
	v_cndmask_b32_e64 v208, 0, v209, s[0:1]
	v_cmp_gt_i32_e64 s[0:1], 2, v16
	s_and_saveexec_b64 s[22:23], s[0:1]
	v_mov_b32_e32 v62, v93
	s_waitcnt lgkmcnt(0)
	v_mov_b32_e32 v63, v57
	v_mov_b32_e32 v60, v56
	v_mul_f32_e32 v64, v57, v61
	v_xor_b32_e32 v210, v208, v64
	v_xor_b32_e32 v211, v208, v65
	v_pk_fma_f32 v[60:61], v[62:63], v[60:61], v[210:211] op_sel_hi:[1,1,0]
	s_nop 0
	v_mov_b32_e32 v93, v60
	s_or_b64 exec, exec, s[22:23]
	s_waitcnt lgkmcnt(1)
	ds_bpermute_b32 v61, v45, v90
	ds_read_b64 v[62:63], v108 offset:48
	v_mov_b32_e32 v209, 0x80000000
	v_cmp_gt_i32_e64 s[0:1], 1, v16
	s_nop 1
	v_cndmask_b32_e64 v208, 0, v209, s[0:1]
	v_cmp_gt_i32_e64 s[0:1], 2, v16
	s_and_saveexec_b64 s[22:23], s[0:1]
	v_mov_b32_e32 v64, v90
	s_waitcnt lgkmcnt(0)
	v_mov_b32_e32 v65, v63
	v_mov_b32_e32 v60, v62
	v_mul_f32_e32 v66, v63, v61
	v_xor_b32_e32 v210, v208, v66
	v_xor_b32_e32 v211, v208, v67
	v_pk_fma_f32 v[60:61], v[64:65], v[60:61], v[210:211] op_sel_hi:[1,1,0]
	s_nop 0
	v_mov_b32_e32 v90, v60
	s_or_b64 exec, exec, s[22:23]
	ds_bpermute_b32 v65, v45, v91
	s_waitcnt lgkmcnt(2)
	ds_read_b64 v[60:61], v108 offset:56
	v_mov_b32_e32 v209, 0x80000000
	v_cmp_gt_i32_e64 s[0:1], 1, v16
	s_nop 1
	v_cndmask_b32_e64 v208, 0, v209, s[0:1]
	v_cmp_gt_i32_e64 s[0:1], 2, v16
	s_and_saveexec_b64 s[22:23], s[0:1]
	v_mov_b32_e32 v66, v91
	s_waitcnt lgkmcnt(0)
	v_mov_b32_e32 v67, v61
	v_mov_b32_e32 v64, v60
	v_mul_f32_e32 v68, v61, v65
	v_xor_b32_e32 v210, v208, v68
	v_xor_b32_e32 v211, v208, v69
	v_pk_fma_f32 v[64:65], v[66:67], v[64:65], v[210:211] op_sel_hi:[1,1,0]
	s_nop 0
	v_mov_b32_e32 v91, v64
	s_or_b64 exec, exec, s[22:23]
	s_waitcnt lgkmcnt(1)
	ds_bpermute_b32 v65, v45, v88
	ds_read_b64 v[66:67], v108 offset:64
	v_mov_b32_e32 v209, 0x80000000
	v_cmp_gt_i32_e64 s[0:1], 1, v16
	s_nop 1
	v_cndmask_b32_e64 v208, 0, v209, s[0:1]
	v_cmp_gt_i32_e64 s[0:1], 2, v16
	s_and_saveexec_b64 s[22:23], s[0:1]
	v_mov_b32_e32 v68, v88
	s_waitcnt lgkmcnt(0)
	v_mov_b32_e32 v69, v67
	v_mov_b32_e32 v64, v66
	v_mul_f32_e32 v70, v67, v65
	v_xor_b32_e32 v210, v208, v70
	v_xor_b32_e32 v211, v208, v71
	v_pk_fma_f32 v[64:65], v[68:69], v[64:65], v[210:211] op_sel_hi:[1,1,0]
	s_nop 0
	v_mov_b32_e32 v88, v64
	s_or_b64 exec, exec, s[22:23]
	ds_bpermute_b32 v69, v45, v89
	s_waitcnt lgkmcnt(2)
	ds_read_b64 v[64:65], v108 offset:72
	v_mov_b32_e32 v209, 0x80000000
	v_cmp_gt_i32_e64 s[0:1], 1, v16
	s_nop 1
	v_cndmask_b32_e64 v208, 0, v209, s[0:1]
	v_cmp_gt_i32_e64 s[0:1], 2, v16
	s_and_saveexec_b64 s[22:23], s[0:1]
	v_mov_b32_e32 v70, v89
	s_waitcnt lgkmcnt(0)
	v_mov_b32_e32 v71, v65
	v_mov_b32_e32 v68, v64
	v_mul_f32_e32 v72, v65, v69
	v_xor_b32_e32 v210, v208, v72
	v_xor_b32_e32 v211, v208, v73
	v_pk_fma_f32 v[68:69], v[70:71], v[68:69], v[210:211] op_sel_hi:[1,1,0]
	s_nop 0
	v_mov_b32_e32 v89, v68
	s_or_b64 exec, exec, s[22:23]
	s_waitcnt lgkmcnt(1)
	ds_bpermute_b32 v69, v45, v86
	ds_read_b64 v[70:71], v108 offset:80
	v_mov_b32_e32 v209, 0x80000000
	v_cmp_gt_i32_e64 s[0:1], 1, v16
	s_nop 1
	v_cndmask_b32_e64 v208, 0, v209, s[0:1]
	v_cmp_gt_i32_e64 s[0:1], 2, v16
	s_and_saveexec_b64 s[22:23], s[0:1]
	v_mov_b32_e32 v72, v86
	s_waitcnt lgkmcnt(0)
	v_mov_b32_e32 v73, v71
	v_mov_b32_e32 v68, v70
	v_mul_f32_e32 v74, v71, v69
	v_xor_b32_e32 v210, v208, v74
	v_xor_b32_e32 v211, v208, v75
	v_pk_fma_f32 v[68:69], v[72:73], v[68:69], v[210:211] op_sel_hi:[1,1,0]
	s_nop 0
	v_mov_b32_e32 v86, v68
	s_or_b64 exec, exec, s[22:23]
	ds_bpermute_b32 v73, v45, v87
	s_waitcnt lgkmcnt(2)
	ds_read_b64 v[68:69], v108 offset:88
	v_mov_b32_e32 v209, 0x80000000
	v_cmp_gt_i32_e64 s[0:1], 1, v16
	s_nop 1
	v_cndmask_b32_e64 v208, 0, v209, s[0:1]
	v_cmp_gt_i32_e64 s[0:1], 2, v16
	s_and_saveexec_b64 s[22:23], s[0:1]
	v_mov_b32_e32 v74, v87
	s_waitcnt lgkmcnt(0)
	v_mov_b32_e32 v75, v69
	v_mov_b32_e32 v72, v68
	v_mul_f32_e32 v76, v69, v73
	v_xor_b32_e32 v210, v208, v76
	v_xor_b32_e32 v211, v208, v77
	v_pk_fma_f32 v[72:73], v[74:75], v[72:73], v[210:211] op_sel_hi:[1,1,0]
	s_nop 0
	v_mov_b32_e32 v87, v72
	s_or_b64 exec, exec, s[22:23]
	s_waitcnt lgkmcnt(1)
	ds_bpermute_b32 v73, v45, v84
	ds_read_b64 v[74:75], v108 offset:96
	v_mov_b32_e32 v209, 0x80000000
	v_cmp_gt_i32_e64 s[0:1], 1, v16
	s_nop 1
	v_cndmask_b32_e64 v208, 0, v209, s[0:1]
	v_cmp_gt_i32_e64 s[0:1], 2, v16
	s_and_saveexec_b64 s[22:23], s[0:1]
	v_mov_b32_e32 v76, v84
	s_waitcnt lgkmcnt(0)
	v_mov_b32_e32 v77, v75
	v_mov_b32_e32 v72, v74
	v_mul_f32_e32 v78, v75, v73
	v_xor_b32_e32 v210, v208, v78
	v_xor_b32_e32 v211, v208, v79
	v_pk_fma_f32 v[72:73], v[76:77], v[72:73], v[210:211] op_sel_hi:[1,1,0]
	s_nop 0
	v_mov_b32_e32 v84, v72
	s_or_b64 exec, exec, s[22:23]
	ds_bpermute_b32 v77, v45, v85
	s_waitcnt lgkmcnt(2)
	ds_read_b64 v[72:73], v108 offset:104
	v_mov_b32_e32 v209, 0x80000000
	v_cmp_gt_i32_e64 s[0:1], 1, v16
	s_nop 1
	v_cndmask_b32_e64 v208, 0, v209, s[0:1]
	v_cmp_gt_i32_e64 s[0:1], 2, v16
	s_and_saveexec_b64 s[22:23], s[0:1]
	v_mov_b32_e32 v78, v85
	s_waitcnt lgkmcnt(0)
	v_mov_b32_e32 v79, v73
	v_mov_b32_e32 v76, v72
	v_mul_f32_e32 v98, v73, v77
	v_xor_b32_e32 v210, v208, v98
	v_xor_b32_e32 v211, v208, v99
	v_pk_fma_f32 v[76:77], v[78:79], v[76:77], v[210:211] op_sel_hi:[1,1,0]
	s_nop 0
	v_mov_b32_e32 v85, v76
	s_or_b64 exec, exec, s[22:23]
	s_waitcnt lgkmcnt(1)
	ds_bpermute_b32 v77, v45, v82
	ds_read_b64 v[78:79], v108 offset:112
	v_mov_b32_e32 v209, 0x80000000
	v_cmp_gt_i32_e64 s[0:1], 1, v16
	s_nop 1
	v_cndmask_b32_e64 v208, 0, v209, s[0:1]
	v_cmp_gt_i32_e64 s[0:1], 2, v16
	s_and_saveexec_b64 s[22:23], s[0:1]
	v_mov_b32_e32 v98, v82
	s_waitcnt lgkmcnt(0)
	v_mov_b32_e32 v99, v79
	v_mov_b32_e32 v76, v78
	v_mul_f32_e32 v82, v79, v77
	v_xor_b32_e32 v210, v208, v82
	v_xor_b32_e32 v211, v208, v83
	v_pk_fma_f32 v[76:77], v[98:99], v[76:77], v[210:211] op_sel_hi:[1,1,0]
	s_nop 0
	v_mov_b32_e32 v82, v76
	s_or_b64 exec, exec, s[22:23]
	ds_bpermute_b32 v99, v45, v83
	s_waitcnt lgkmcnt(2)
	ds_read_b64 v[76:77], v108 offset:120
	v_mov_b32_e32 v209, 0x80000000
	v_cmp_gt_i32_e64 s[0:1], 1, v16
	s_nop 1
	v_cndmask_b32_e64 v208, 0, v209, s[0:1]
	v_cmp_gt_i32_e64 s[0:1], 2, v16
	s_and_saveexec_b64 s[22:23], s[0:1]
	v_mov_b32_e32 v100, v83
	s_waitcnt lgkmcnt(0)
	v_mov_b32_e32 v101, v77
	v_mov_b32_e32 v98, v76
	v_mul_f32_e32 v102, v77, v99
	v_xor_b32_e32 v210, v208, v102
	v_xor_b32_e32 v211, v208, v103
	v_pk_fma_f32 v[98:99], v[100:101], v[98:99], v[210:211] op_sel_hi:[1,1,0]
	s_nop 0
	v_mov_b32_e32 v83, v98
	s_or_b64 exec, exec, s[22:23]
	v_cvt_pk_bf16_f32 v96, v96, v97
	v_cvt_pk_bf16_f32 v97, v94, v95
	v_cvt_pk_bf16_f32 v98, v92, v93
	s_waitcnt lgkmcnt(1)
	v_cvt_pk_bf16_f32 v99, v90, v91
	v_cvt_pk_bf16_f32 v88, v88, v89
	v_cvt_pk_bf16_f32 v89, v86, v87
	v_cvt_pk_bf16_f32 v90, v84, v85
	v_cvt_pk_bf16_f32 v91, v82, v83
	global_store_dwordx4 v[80:81], v[96:99], off
	global_store_dwordx4 v[80:81], v[88:91], off offset:16
	v_lshlrev_b64 v[80:81], 8, v[42:43]
	v_lshl_add_u64 v[80:81], v[50:51], 0, v[80:81]
	v_mov_b32_e32 v90, 0
	v_mov_b32_e32 v91, 0
	v_mov_b32_e32 v82, 0
	v_mov_b32_e32 v83, 0
	v_mov_b32_e32 v84, 0
	v_mov_b32_e32 v85, 0
	v_mov_b32_e32 v86, 0
	v_mov_b32_e32 v87, 0
	v_mov_b32_e32 v88, 0
	v_mov_b32_e32 v89, 0
	v_mov_b32_e32 v100, 0
	v_mov_b32_e32 v101, 0
	v_mov_b32_e32 v102, 0
	v_mov_b32_e32 v103, 0
	v_mov_b32_e32 v104, 0
	v_mov_b32_e32 v105, 0
	s_and_saveexec_b64 s[0:1], s[4:5]
	s_cbranch_execz .LBB0_744
	v_mov_b32_e32 v84, v184
	v_mov_b32_e32 v85, v185
	v_mov_b32_e32 v86, v186
	v_mov_b32_e32 v87, v187
	v_mov_b32_e32 v92, v188
	v_mov_b32_e32 v93, v189
	v_mov_b32_e32 v94, v190
	v_mov_b32_e32 v95, v191
	v_lshlrev_b32_e32 v90, 16, v84
	v_and_b32_e32 v91, 0xffff0000, v84
	v_lshlrev_b32_e32 v82, 16, v85
	v_and_b32_e32 v83, 0xffff0000, v85
	v_lshlrev_b32_e32 v84, 16, v86
	v_and_b32_e32 v85, 0xffff0000, v86
	v_lshlrev_b32_e32 v86, 16, v87
	v_and_b32_e32 v87, 0xffff0000, v87
	v_lshlrev_b32_e32 v88, 16, v92
	v_and_b32_e32 v89, 0xffff0000, v92
	v_lshlrev_b32_e32 v100, 16, v93
	v_and_b32_e32 v101, 0xffff0000, v93
	v_lshlrev_b32_e32 v102, 16, v94
	v_and_b32_e32 v103, 0xffff0000, v94
	v_lshlrev_b32_e32 v104, 16, v95
	v_and_b32_e32 v105, 0xffff0000, v95

.LBB0_750:
	s_or_b64 exec, exec, s[0:1]
	ds_bpermute_b32 v1, v45, v97
	v_mov_b32_e32 v209, 0x80000000
	v_cmp_gt_i32_e64 s[0:1], 1, v16
	s_nop 1
	v_cndmask_b32_e64 v208, 0, v209, s[0:1]
	v_cmp_gt_i32_e64 s[0:1], 2, v16
	s_and_saveexec_b64 s[22:23], s[0:1]
	v_mov_b32_e32 v0, v97
	v_mul_f32_e32 v98, v2, v97
	s_waitcnt lgkmcnt(0)
	v_xor_b32_e32 v210, v208, v2
	v_xor_b32_e32 v211, v208, v3
	v_pk_fma_f32 v[0:1], v[210:211], v[0:1], v[98:99] op_sel_hi:[1,1,0]
	s_nop 0
	v_mov_b32_e32 v97, v1
	s_or_b64 exec, exec, s[22:23]
	s_waitcnt lgkmcnt(0)
	ds_bpermute_b32 v1, v45, v94
	v_mov_b32_e32 v209, 0x80000000
	v_cmp_gt_i32_e64 s[0:1], 1, v16
	s_nop 1
	v_cndmask_b32_e64 v208, 0, v209, s[0:1]
	v_cmp_gt_i32_e64 s[0:1], 2, v16
	s_and_saveexec_b64 s[22:23], s[0:1]
	v_mov_b32_e32 v0, v94
	s_waitcnt lgkmcnt(0)
	v_mul_f32_e32 v2, v7, v1
	v_xor_b32_e32 v210, v208, v2
	v_xor_b32_e32 v211, v208, v3
	v_pk_fma_f32 v[0:1], v[6:7], v[0:1], v[210:211] op_sel_hi:[1,1,0]
	s_nop 0
	v_mov_b32_e32 v94, v0
	s_or_b64 exec, exec, s[22:23]
	s_waitcnt lgkmcnt(0)
	ds_bpermute_b32 v1, v45, v95
	v_mov_b32_e32 v209, 0x80000000
	v_cmp_gt_i32_e64 s[0:1], 1, v16
	s_nop 1
	v_cndmask_b32_e64 v208, 0, v209, s[0:1]
	v_cmp_gt_i32_e64 s[0:1], 2, v16
	s_and_saveexec_b64 s[22:23], s[0:1]
	v_mov_b32_e32 v0, v95
	s_waitcnt lgkmcnt(0)
	v_mul_f32_e32 v2, v5, v1
	v_xor_b32_e32 v210, v208, v2
	v_xor_b32_e32 v211, v208, v3
	v_pk_fma_f32 v[0:1], v[4:5], v[0:1], v[210:211] op_sel_hi:[1,1,0]
	s_nop 0
	v_mov_b32_e32 v95, v0
	s_or_b64 exec, exec, s[22:23]
	s_waitcnt lgkmcnt(0)
	ds_bpermute_b32 v1, v45, v92
	v_mov_b32_e32 v209, 0x80000000
	v_cmp_gt_i32_e64 s[0:1], 1, v16
	s_nop 1
	v_cndmask_b32_e64 v208, 0, v209, s[0:1]
	v_cmp_gt_i32_e64 s[0:1], 2, v16
	s_and_saveexec_b64 s[22:23], s[0:1]
	v_mov_b32_e32 v0, v92
	s_waitcnt lgkmcnt(0)
	v_mul_f32_e32 v2, v59, v1
	v_xor_b32_e32 v210, v208, v2
	v_xor_b32_e32 v211, v208, v3
	v_pk_fma_f32 v[0:1], v[58:59], v[0:1], v[210:211] op_sel_hi:[1,1,0]
	s_nop 0
	v_mov_b32_e32 v92, v0
	s_or_b64 exec, exec, s[22:23]
	s_waitcnt lgkmcnt(0)
	ds_bpermute_b32 v1, v45, v93
	v_mov_b32_e32 v209, 0x80000000
	v_cmp_gt_i32_e64 s[0:1], 1, v16
	s_nop 1
	v_cndmask_b32_e64 v208, 0, v209, s[0:1]
	v_cmp_gt_i32_e64 s[0:1], 2, v16
	s_and_saveexec_b64 s[22:23], s[0:1]
	v_mov_b32_e32 v0, v93
	s_waitcnt lgkmcnt(0)
	v_mul_f32_e32 v2, v57, v1
	v_xor_b32_e32 v210, v208, v2
	v_xor_b32_e32 v211, v208, v3
	v_pk_fma_f32 v[0:1], v[56:57], v[0:1], v[210:211] op_sel_hi:[1,1,0]
	s_nop 0
	v_mov_b32_e32 v93, v0
	s_or_b64 exec, exec, s[22:23]
	s_waitcnt lgkmcnt(0)
	ds_bpermute_b32 v1, v45, v90
	v_mov_b32_e32 v209, 0x80000000
	v_cmp_gt_i32_e64 s[0:1], 1, v16
	s_nop 1
	v_cndmask_b32_e64 v208, 0, v209, s[0:1]
	v_cmp_gt_i32_e64 s[0:1], 2, v16
	s_and_saveexec_b64 s[22:23], s[0:1]
	v_mov_b32_e32 v0, v90
	s_waitcnt lgkmcnt(0)
	v_mul_f32_e32 v2, v63, v1
	v_xor_b32_e32 v210, v208, v2
	v_xor_b32_e32 v211, v208, v3
	v_pk_fma_f32 v[0:1], v[62:63], v[0:1], v[210:211] op_sel_hi:[1,1,0]
	s_nop 0
	v_mov_b32_e32 v90, v0
	s_or_b64 exec, exec, s[22:23]
	s_waitcnt lgkmcnt(0)
	ds_bpermute_b32 v1, v45, v91
	v_mov_b32_e32 v209, 0x80000000
	v_cmp_gt_i32_e64 s[0:1], 1, v16
	s_nop 1
	v_cndmask_b32_e64 v208, 0, v209, s[0:1]
	v_cmp_gt_i32_e64 s[0:1], 2, v16
	s_and_saveexec_b64 s[22:23], s[0:1]
	v_mov_b32_e32 v0, v91
	s_waitcnt lgkmcnt(0)
	v_mul_f32_e32 v2, v61, v1
	v_xor_b32_e32 v210, v208, v2
	v_xor_b32_e32 v211, v208, v3
	v_pk_fma_f32 v[0:1], v[60:61], v[0:1], v[210:211] op_sel_hi:[1,1,0]
	s_nop 0
	v_mov_b32_e32 v91, v0
	s_or_b64 exec, exec, s[22:23]
	s_waitcnt lgkmcnt(0)
	ds_bpermute_b32 v1, v45, v88
	v_mov_b32_e32 v209, 0x80000000
	v_cmp_gt_i32_e64 s[0:1], 1, v16
	s_nop 1
	v_cndmask_b32_e64 v208, 0, v209, s[0:1]
	v_cmp_gt_i32_e64 s[0:1], 2, v16
	s_and_saveexec_b64 s[22:23], s[0:1]
	v_mov_b32_e32 v0, v88
	s_waitcnt lgkmcnt(0)
	v_mul_f32_e32 v2, v67, v1
	v_xor_b32_e32 v210, v208, v2
	v_xor_b32_e32 v211, v208, v3
	v_pk_fma_f32 v[0:1], v[66:67], v[0:1], v[210:211] op_sel_hi:[1,1,0]
	s_nop 0
	v_mov_b32_e32 v88, v0
	s_or_b64 exec, exec, s[22:23]
	s_waitcnt lgkmcnt(0)
	ds_bpermute_b32 v1, v45, v89
	v_mov_b32_e32 v209, 0x80000000
	v_cmp_gt_i32_e64 s[0:1], 1, v16
	s_nop 1
	v_cndmask_b32_e64 v208, 0, v209, s[0:1]
	v_cmp_gt_i32_e64 s[0:1], 2, v16
	s_and_saveexec_b64 s[22:23], s[0:1]
	v_mov_b32_e32 v0, v89
	s_waitcnt lgkmcnt(0)
	v_mul_f32_e32 v2, v65, v1
	v_xor_b32_e32 v210, v208, v2
	v_xor_b32_e32 v211, v208, v3
	v_pk_fma_f32 v[0:1], v[64:65], v[0:1], v[210:211] op_sel_hi:[1,1,0]
	s_nop 0
	v_mov_b32_e32 v89, v0
	s_or_b64 exec, exec, s[22:23]
	s_waitcnt lgkmcnt(0)
	ds_bpermute_b32 v1, v45, v86
	v_mov_b32_e32 v209, 0x80000000
	v_cmp_gt_i32_e64 s[0:1], 1, v16
	s_nop 1
	v_cndmask_b32_e64 v208, 0, v209, s[0:1]
	v_cmp_gt_i32_e64 s[0:1], 2, v16
	s_and_saveexec_b64 s[22:23], s[0:1]
	v_mov_b32_e32 v0, v86
	s_waitcnt lgkmcnt(0)
	v_mul_f32_e32 v2, v71, v1
	v_xor_b32_e32 v210, v208, v2
	v_xor_b32_e32 v211, v208, v3
	v_pk_fma_f32 v[0:1], v[70:71], v[0:1], v[210:211] op_sel_hi:[1,1,0]
	s_nop 0
	v_mov_b32_e32 v86, v0
	s_or_b64 exec, exec, s[22:23]
	s_waitcnt lgkmcnt(0)
	ds_bpermute_b32 v1, v45, v87
	v_mov_b32_e32 v209, 0x80000000
	v_cmp_gt_i32_e64 s[0:1], 1, v16
	s_nop 1
	v_cndmask_b32_e64 v208, 0, v209, s[0:1]
	v_cmp_gt_i32_e64 s[0:1], 2, v16
	s_and_saveexec_b64 s[22:23], s[0:1]
	v_mov_b32_e32 v0, v87
	s_waitcnt lgkmcnt(0)
	v_mul_f32_e32 v2, v69, v1
	v_xor_b32_e32 v210, v208, v2
	v_xor_b32_e32 v211, v208, v3
	v_pk_fma_f32 v[0:1], v[68:69], v[0:1], v[210:211] op_sel_hi:[1,1,0]
	s_nop 0
	v_mov_b32_e32 v87, v0
	s_or_b64 exec, exec, s[22:23]
	s_waitcnt lgkmcnt(0)
	ds_bpermute_b32 v1, v45, v84
	v_mov_b32_e32 v209, 0x80000000
	v_cmp_gt_i32_e64 s[0:1], 1, v16
	s_nop 1
	v_cndmask_b32_e64 v208, 0, v209, s[0:1]
	v_cmp_gt_i32_e64 s[0:1], 2, v16
	s_and_saveexec_b64 s[22:23], s[0:1]
	v_mov_b32_e32 v0, v84
	s_waitcnt lgkmcnt(0)
	v_mul_f32_e32 v2, v75, v1
	v_xor_b32_e32 v210, v208, v2
	v_xor_b32_e32 v211, v208, v3
	v_pk_fma_f32 v[0:1], v[74:75], v[0:1], v[210:211] op_sel_hi:[1,1,0]
	s_nop 0
	v_mov_b32_e32 v84, v0
	s_or_b64 exec, exec, s[22:23]
	s_waitcnt lgkmcnt(0)
	ds_bpermute_b32 v1, v45, v85
	v_mov_b32_e32 v209, 0x80000000
	v_cmp_gt_i32_e64 s[0:1], 1, v16
	s_nop 1
	v_cndmask_b32_e64 v208, 0, v209, s[0:1]
	v_cmp_gt_i32_e64 s[0:1], 2, v16
	s_and_saveexec_b64 s[22:23], s[0:1]
	v_mov_b32_e32 v0, v85
	s_waitcnt lgkmcnt(0)
	v_mul_f32_e32 v2, v73, v1
	v_xor_b32_e32 v210, v208, v2
	v_xor_b32_e32 v211, v208, v3
	v_pk_fma_f32 v[0:1], v[72:73], v[0:1], v[210:211] op_sel_hi:[1,1,0]
	s_nop 0
	v_mov_b32_e32 v85, v0
	s_or_b64 exec, exec, s[22:23]
	s_waitcnt lgkmcnt(0)
	ds_bpermute_b32 v1, v45, v82
	v_mov_b32_e32 v209, 0x80000000
	v_cmp_gt_i32_e64 s[0:1], 1, v16
	s_nop 1
	v_cndmask_b32_e64 v208, 0, v209, s[0:1]
	v_cmp_gt_i32_e64 s[0:1], 2, v16
	s_and_saveexec_b64 s[22:23], s[0:1]
	v_mov_b32_e32 v0, v82
	s_waitcnt lgkmcnt(0)
	v_mul_f32_e32 v2, v79, v1
	v_xor_b32_e32 v210, v208, v2
	v_xor_b32_e32 v211, v208, v3
	v_pk_fma_f32 v[0:1], v[78:79], v[0:1], v[210:211] op_sel_hi:[1,1,0]
	s_nop 0
	v_mov_b32_e32 v82, v0
	s_or_b64 exec, exec, s[22:23]
	s_waitcnt lgkmcnt(0)
	ds_bpermute_b32 v1, v45, v83
	v_cmp_lt_i32_e64 s[0:1], 0, v16
	s_and_saveexec_b64 s[22:23], s[0:1]
	s_xor_b64 s[22:23], exec, s[22:23]
	s_cbranch_execz .LBB0_937
	v_cmp_eq_u32_e64 s[0:1], 1, v16
	s_and_saveexec_b64 s[24:25], s[0:1]
	s_cbranch_execz .LBB0_837
	v_mov_b32_e32 v0, v83
	s_waitcnt lgkmcnt(0)
	v_mul_f32_e32 v2, v77, v1
	v_pk_fma_f32 v[0:1], v[76:77], v[0:1], v[2:3] op_sel_hi:[1,1,0]
	s_nop 0
	v_mov_b32_e32 v83, v0

.LBB0_846:
	s_or_b64 exec, exec, s[0:1]
	ds_bpermute_b32 v63, v45, v1
	v_mov_b32_e32 v0, v60
	s_waitcnt lgkmcnt(1)
	ds_read_b64 v[60:61], v108 offset:136
	v_mov_b32_e32 v209, 0x80000000
	v_cmp_gt_i32_e64 s[0:1], 1, v16
	s_nop 1
	v_cndmask_b32_e64 v208, 0, v209, s[0:1]
	v_cmp_gt_i32_e64 s[0:1], 2, v16
	s_and_saveexec_b64 s[22:23], s[0:1]
	v_mov_b32_e32 v64, v1
	s_waitcnt lgkmcnt(0)
	v_mov_b32_e32 v65, v61
	v_mov_b32_e32 v62, v60
	v_mul_f32_e32 v66, v1, v60
	v_xor_b32_e32 v210, v208, v64
	v_xor_b32_e32 v211, v208, v65
	v_pk_fma_f32 v[62:63], v[210:211], v[62:63], v[66:67] op_sel_hi:[1,1,0]
	s_nop 0
	v_mov_b32_e32 v1, v63
	s_or_b64 exec, exec, s[22:23]
	s_waitcnt lgkmcnt(1)
	ds_bpermute_b32 v63, v45, v2
	ds_read_b64 v[64:65], v108 offset:144
	v_mov_b32_e32 v209, 0x80000000
	v_cmp_gt_i32_e64 s[0:1], 1, v16
	s_nop 1
	v_cndmask_b32_e64 v208, 0, v209, s[0:1]
	v_cmp_gt_i32_e64 s[0:1], 2, v16
	s_and_saveexec_b64 s[22:23], s[0:1]
	v_mov_b32_e32 v66, v2
	s_waitcnt lgkmcnt(0)
	v_mov_b32_e32 v67, v65
	v_mov_b32_e32 v62, v64
	v_mul_f32_e32 v2, v65, v63
	v_xor_b32_e32 v210, v208, v2
	v_xor_b32_e32 v211, v208, v3
	v_pk_fma_f32 v[62:63], v[66:67], v[62:63], v[210:211] op_sel_hi:[1,1,0]
	s_nop 0
	v_mov_b32_e32 v2, v62
	s_or_b64 exec, exec, s[22:23]
	ds_bpermute_b32 v67, v45, v3
	s_waitcnt lgkmcnt(2)
	ds_read_b64 v[62:63], v108 offset:152
	v_mov_b32_e32 v209, 0x80000000
	v_cmp_gt_i32_e64 s[0:1], 1, v16
	s_nop 1
	v_cndmask_b32_e64 v208, 0, v209, s[0:1]
	v_cmp_gt_i32_e64 s[0:1], 2, v16
	s_and_saveexec_b64 s[22:23], s[0:1]
	v_mov_b32_e32 v68, v3
	s_waitcnt lgkmcnt(0)
	v_mov_b32_e32 v69, v63
	v_mov_b32_e32 v66, v62
	v_mul_f32_e32 v70, v63, v67
	v_xor_b32_e32 v210, v208, v70
	v_xor_b32_e32 v211, v208, v71
	v_pk_fma_f32 v[66:67], v[68:69], v[66:67], v[210:211] op_sel_hi:[1,1,0]
	s_nop 0
	v_mov_b32_e32 v3, v66
	s_or_b64 exec, exec, s[22:23]
	s_waitcnt lgkmcnt(1)
	ds_bpermute_b32 v67, v45, v4
	ds_read_b64 v[68:69], v108 offset:160
	v_mov_b32_e32 v209, 0x80000000
	v_cmp_gt_i32_e64 s[0:1], 1, v16
	s_nop 1
	v_cndmask_b32_e64 v208, 0, v209, s[0:1]
	v_cmp_gt_i32_e64 s[0:1], 2, v16
	s_and_saveexec_b64 s[22:23], s[0:1]
	v_mov_b32_e32 v70, v4
	s_waitcnt lgkmcnt(0)
	v_mov_b32_e32 v71, v69
	v_mov_b32_e32 v66, v68
	v_mul_f32_e32 v4, v69, v67
	v_xor_b32_e32 v210, v208, v4
	v_xor_b32_e32 v211, v208, v5
	v_pk_fma_f32 v[66:67], v[70:71], v[66:67], v[210:211] op_sel_hi:[1,1,0]
	s_nop 0
	v_mov_b32_e32 v4, v66
	s_or_b64 exec, exec, s[22:23]
	ds_bpermute_b32 v71, v45, v5
	s_waitcnt lgkmcnt(2)
	ds_read_b64 v[66:67], v108 offset:168
	v_mov_b32_e32 v209, 0x80000000
	v_cmp_gt_i32_e64 s[0:1], 1, v16
	s_nop 1
	v_cndmask_b32_e64 v208, 0, v209, s[0:1]
	v_cmp_gt_i32_e64 s[0:1], 2, v16
	s_and_saveexec_b64 s[22:23], s[0:1]
	v_mov_b32_e32 v72, v5
	s_waitcnt lgkmcnt(0)
	v_mov_b32_e32 v73, v67
	v_mov_b32_e32 v70, v66
	v_mul_f32_e32 v74, v67, v71
	v_xor_b32_e32 v210, v208, v74
	v_xor_b32_e32 v211, v208, v75
	v_pk_fma_f32 v[70:71], v[72:73], v[70:71], v[210:211] op_sel_hi:[1,1,0]
	s_nop 0
	v_mov_b32_e32 v5, v70
	s_or_b64 exec, exec, s[22:23]
	s_waitcnt lgkmcnt(1)
	ds_bpermute_b32 v71, v45, v6
	ds_read_b64 v[72:73], v108 offset:176
	v_mov_b32_e32 v209, 0x80000000
	v_cmp_gt_i32_e64 s[0:1], 1, v16
	s_nop 1
	v_cndmask_b32_e64 v208, 0, v209, s[0:1]
	v_cmp_gt_i32_e64 s[0:1], 2, v16
	s_and_saveexec_b64 s[22:23], s[0:1]
	v_mov_b32_e32 v74, v6
	s_waitcnt lgkmcnt(0)
	v_mov_b32_e32 v75, v73
	v_mov_b32_e32 v70, v72
	v_mul_f32_e32 v6, v73, v71
	v_xor_b32_e32 v210, v208, v6
	v_xor_b32_e32 v211, v208, v7
	v_pk_fma_f32 v[70:71], v[74:75], v[70:71], v[210:211] op_sel_hi:[1,1,0]
	s_nop 0
	v_mov_b32_e32 v6, v70
	s_or_b64 exec, exec, s[22:23]
	ds_bpermute_b32 v75, v45, v7
	s_waitcnt lgkmcnt(2)
	ds_read_b64 v[70:71], v108 offset:184
	v_mov_b32_e32 v209, 0x80000000
	v_cmp_gt_i32_e64 s[0:1], 1, v16
	s_nop 1
	v_cndmask_b32_e64 v208, 0, v209, s[0:1]
	v_cmp_gt_i32_e64 s[0:1], 2, v16
	s_and_saveexec_b64 s[22:23], s[0:1]
	v_mov_b32_e32 v76, v7
	s_waitcnt lgkmcnt(0)
	v_mov_b32_e32 v77, v71
	v_mov_b32_e32 v74, v70
	v_mul_f32_e32 v78, v71, v75
	v_xor_b32_e32 v210, v208, v78
	v_xor_b32_e32 v211, v208, v79
	v_pk_fma_f32 v[74:75], v[76:77], v[74:75], v[210:211] op_sel_hi:[1,1,0]
	s_nop 0
	v_mov_b32_e32 v7, v74
	s_or_b64 exec, exec, s[22:23]
	v_cvt_pk_bf16_f32 v0, v0, v1
	v_cvt_pk_bf16_f32 v1, v2, v3
	v_cvt_pk_bf16_f32 v2, v4, v5
	v_cvt_pk_bf16_f32 v3, v6, v7
	global_store_dwordx4 v[58:59], v[0:3], off
	s_nop 1
	v_lshlrev_b64 v[0:1], 7, v[42:43]
	v_lshl_add_u64 v[58:59], v[54:55], 0, v[0:1]
	v_mov_b32_e32 v0, 0
	v_mov_b32_e32 v1, v0
	v_mov_b32_e32 v2, v0
	v_mov_b32_e32 v3, v0
	v_mov_b32_e32 v4, v0
	v_mov_b32_e32 v5, v0
	v_mov_b32_e32 v6, v0
	v_mov_b32_e32 v7, v0
	s_and_saveexec_b64 s[0:1], s[4:5]
	s_cbranch_execz .LBB0_890
	v_mov_b32_e32 v4, v196
	v_mov_b32_e32 v5, v197
	v_mov_b32_e32 v6, v198
	v_mov_b32_e32 v7, v199
	v_lshlrev_b32_e32 v0, 16, v4
	v_and_b32_e32 v1, 0xffff0000, v4
	v_lshlrev_b32_e32 v2, 16, v5
	v_and_b32_e32 v3, 0xffff0000, v5
	v_lshlrev_b32_e32 v4, 16, v6
	v_and_b32_e32 v5, 0xffff0000, v6
	v_lshlrev_b32_e32 v6, 16, v7
	v_and_b32_e32 v7, 0xffff0000, v7
.LBB0_890:
	s_or_b64 exec, exec, s[0:1]
	s_waitcnt lgkmcnt(1)
	ds_bpermute_b32 v75, v45, v0
	v_mov_b32_e32 v209, 0x80000000
	v_cmp_gt_i32_e64 s[0:1], 1, v16
	s_nop 1
	v_cndmask_b32_e64 v208, 0, v209, s[0:1]
	v_cmp_gt_i32_e64 s[0:1], 2, v16
	s_and_saveexec_b64 s[22:23], s[0:1]
	v_mov_b32_e32 v74, v0
	s_waitcnt lgkmcnt(0)
	v_pk_mul_f32 v[56:57], v[56:57], v[74:75]
	s_nop 0
	v_xor_b32_e32 v210, v208, v57
	v_add_f32_e32 v0, v56, v210
	s_or_b64 exec, exec, s[22:23]
	ds_bpermute_b32 v57, v45, v1
	v_mov_b32_e32 v209, 0x80000000
	v_cmp_gt_i32_e64 s[0:1], 1, v16
	s_nop 1
	v_cndmask_b32_e64 v208, 0, v209, s[0:1]
	v_cmp_gt_i32_e64 s[0:1], 2, v16
	s_and_saveexec_b64 s[22:23], s[0:1]
	v_mov_b32_e32 v56, v1
	v_mul_f32_e32 v74, v60, v1
	s_waitcnt lgkmcnt(0)
	v_xor_b32_e32 v210, v208, v60
	v_xor_b32_e32 v211, v208, v61
	v_pk_fma_f32 v[56:57], v[210:211], v[56:57], v[74:75] op_sel_hi:[1,1,0]
	s_nop 0
	v_mov_b32_e32 v1, v57
	s_or_b64 exec, exec, s[22:23]
	s_waitcnt lgkmcnt(0)
	ds_bpermute_b32 v57, v45, v2
	v_mov_b32_e32 v209, 0x80000000
	v_cmp_gt_i32_e64 s[0:1], 1, v16
	s_nop 1
	v_cndmask_b32_e64 v208, 0, v209, s[0:1]
	v_cmp_gt_i32_e64 s[0:1], 2, v16
	s_and_saveexec_b64 s[22:23], s[0:1]
	v_mov_b32_e32 v56, v2
	s_waitcnt lgkmcnt(0)
	v_mul_f32_e32 v2, v65, v57
	v_xor_b32_e32 v210, v208, v2
	v_xor_b32_e32 v211, v208, v3
	v_pk_fma_f32 v[56:57], v[64:65], v[56:57], v[210:211] op_sel_hi:[1,1,0]
	s_nop 0
	v_mov_b32_e32 v2, v56
	s_or_b64 exec, exec, s[22:23]
	s_waitcnt lgkmcnt(0)
	ds_bpermute_b32 v57, v45, v3
	v_mov_b32_e32 v209, 0x80000000
	v_cmp_gt_i32_e64 s[0:1], 1, v16
	s_nop 1
	v_cndmask_b32_e64 v208, 0, v209, s[0:1]
	v_cmp_gt_i32_e64 s[0:1], 2, v16
	s_and_saveexec_b64 s[22:23], s[0:1]
	v_mov_b32_e32 v56, v3
	s_waitcnt lgkmcnt(0)
	v_mul_f32_e32 v60, v63, v57
	v_xor_b32_e32 v210, v208, v60
	v_xor_b32_e32 v211, v208, v61
	v_pk_fma_f32 v[56:57], v[62:63], v[56:57], v[210:211] op_sel_hi:[1,1,0]
	s_nop 0
	v_mov_b32_e32 v3, v56
	s_or_b64 exec, exec, s[22:23]
	s_waitcnt lgkmcnt(0)
	ds_bpermute_b32 v57, v45, v4
	v_mov_b32_e32 v209, 0x80000000
	v_cmp_gt_i32_e64 s[0:1], 1, v16
	s_nop 1
	v_cndmask_b32_e64 v208, 0, v209, s[0:1]
	v_cmp_gt_i32_e64 s[0:1], 2, v16
	s_and_saveexec_b64 s[22:23], s[0:1]
	v_mov_b32_e32 v56, v4
	s_waitcnt lgkmcnt(0)
	v_mul_f32_e32 v4, v69, v57
	v_xor_b32_e32 v210, v208, v4
	v_xor_b32_e32 v211, v208, v5
	v_pk_fma_f32 v[56:57], v[68:69], v[56:57], v[210:211] op_sel_hi:[1,1,0]
	s_nop 0
	v_mov_b32_e32 v4, v56
	s_or_b64 exec, exec, s[22:23]
	s_waitcnt lgkmcnt(0)
	ds_bpermute_b32 v57, v45, v5
	v_mov_b32_e32 v209, 0x80000000
	v_cmp_gt_i32_e64 s[0:1], 1, v16
	s_nop 1
	v_cndmask_b32_e64 v208, 0, v209, s[0:1]
	v_cmp_gt_i32_e64 s[0:1], 2, v16
	s_and_saveexec_b64 s[22:23], s[0:1]
	v_mov_b32_e32 v56, v5
	s_waitcnt lgkmcnt(0)
	v_mul_f32_e32 v60, v67, v57
	v_xor_b32_e32 v210, v208, v60
	v_xor_b32_e32 v211, v208, v61
	v_pk_fma_f32 v[56:57], v[66:67], v[56:57], v[210:211] op_sel_hi:[1,1,0]
	s_nop 0
	v_mov_b32_e32 v5, v56
	s_or_b64 exec, exec, s[22:23]
	s_waitcnt lgkmcnt(0)
	ds_bpermute_b32 v57, v45, v6
	v_mov_b32_e32 v209, 0x80000000
	v_cmp_gt_i32_e64 s[0:1], 1, v16
	s_nop 1
	v_cndmask_b32_e64 v208, 0, v209, s[0:1]
	v_cmp_gt_i32_e64 s[0:1], 2, v16
	s_and_saveexec_b64 s[22:23], s[0:1]
	v_mov_b32_e32 v56, v6
	s_waitcnt lgkmcnt(0)
	v_mul_f32_e32 v6, v73, v57
	v_xor_b32_e32 v210, v208, v6
	v_xor_b32_e32 v211, v208, v7
	v_pk_fma_f32 v[56:57], v[72:73], v[56:57], v[210:211] op_sel_hi:[1,1,0]
	s_nop 0
	v_mov_b32_e32 v6, v56
	s_or_b64 exec, exec, s[22:23]
	s_waitcnt lgkmcnt(0)
	ds_bpermute_b32 v57, v45, v7
	v_cmp_lt_i32_e64 s[0:1], 0, v16
	s_and_saveexec_b64 s[22:23], s[0:1]
	s_xor_b64 s[22:23], exec, s[22:23]
	s_cbranch_execz .LBB0_939
	v_cmp_eq_u32_e64 s[0:1], 1, v16
	s_and_saveexec_b64 s[24:25], s[0:1]
	s_cbranch_execz .LBB0_935
	v_mov_b32_e32 v56, v7
	s_waitcnt lgkmcnt(0)
	v_mul_f32_e32 v60, v71, v57
	v_pk_fma_f32 v[56:57], v[70:71], v[56:57], v[60:61] op_sel_hi:[1,1,0]
	s_nop 0
	v_mov_b32_e32 v7, v56
